# K/Q-projection GEMM K-loop LDS-DMA loads also use scalar base + 32-bit lane offset (on top of FFN-in and residual-GEMM loops, blocked hidden layout)
# speedup vs baseline: 1.0174x; 1.0041x over previous
.LBB0_87:
	s_add_u32 s30, s34, 0xfffc0080
	s_addc_u32 s31, s35, -1
	s_cmp_eq_u32 s55, 12
	s_cselect_b32 s37, s23, s31
	s_cselect_b32 s36, s44, s30
	s_cselect_b32 s31, s25, s54
	s_cselect_b32 s30, s45, s46
	s_add_i32 s56, 0, 0x14000
	v_add_u32_e32 v142, s62, v164
	v_add_u32_e32 v160, s56, v164
	ds_read_b128 v[130:133], v142
	ds_read_b128 v[134:137], v142 offset:1024
	ds_read_b128 v[138:141], v142 offset:2048
	ds_read_b128 v[142:145], v142 offset:3072
	ds_read_b128 v[168:171], v160
	ds_read_b128 v[172:175], v160 offset:1024
	ds_read_b128 v[176:179], v160 offset:2048
	ds_read_b128 v[180:183], v160 offset:3072
	s_add_i32 m0, s49, 0xc000
	ds_read_b128 v[184:187], v167
	ds_read_b128 v[198:201], v167 offset:1024
	ds_read_b128 v[202:205], v167 offset:2048
	ds_read_b128 v[206:209], v167 offset:3072
	ds_read_b128 v[210:213], v167 offset:4096
	ds_read_b128 v[214:217], v167 offset:5120
	ds_read_b128 v[218:221], v167 offset:6144
	ds_read_b128 v[222:225], v167 offset:7168
	global_load_lds_dwordx4 v156, s[34:35]
	s_add_i32 m0, s49, 0xe000
	s_nop 0
	global_load_lds_dwordx4 v158, s[34:35]
	s_waitcnt vmcnt(8)
	s_waitcnt lgkmcnt(0)
	s_barrier
	s_setprio 1
	s_waitcnt lgkmcnt(0)
	v_mfma_f32_16x16x32_bf16 v[118:121], v[130:133], v[184:187], v[118:121]
	v_mfma_f32_16x16x32_bf16 v[114:117], v[138:141], v[184:187], v[114:117]
	v_mfma_f32_16x16x32_bf16 v[102:105], v[130:133], v[202:205], v[102:105]
	v_mfma_f32_16x16x32_bf16 v[98:101], v[138:141], v[202:205], v[98:101]
	v_mfma_f32_16x16x32_bf16 v[86:89], v[130:133], v[210:213], v[86:89]
	v_mfma_f32_16x16x32_bf16 v[82:85], v[138:141], v[210:213], v[82:85]
	v_mfma_f32_16x16x32_bf16 v[54:57], v[130:133], v[218:221], v[54:57]
	v_mfma_f32_16x16x32_bf16 v[50:53], v[138:141], v[218:221], v[50:53]
	v_mfma_f32_16x16x32_bf16 v[118:121], v[134:137], v[198:201], v[118:121]
	v_mfma_f32_16x16x32_bf16 v[114:117], v[142:145], v[198:201], v[114:117]
	v_mfma_f32_16x16x32_bf16 v[102:105], v[134:137], v[206:209], v[102:105]
	v_mfma_f32_16x16x32_bf16 v[98:101], v[142:145], v[206:209], v[98:101]
	v_mfma_f32_16x16x32_bf16 v[86:89], v[134:137], v[214:217], v[86:89]
	v_mfma_f32_16x16x32_bf16 v[82:85], v[142:145], v[214:217], v[82:85]
	v_mfma_f32_16x16x32_bf16 v[54:57], v[134:137], v[222:225], v[54:57]
	v_mfma_f32_16x16x32_bf16 v[50:53], v[142:145], v[222:225], v[50:53]
	s_setprio 0
	s_setprio 1
	v_mfma_f32_16x16x32_bf16 v[126:129], v[168:171], v[184:187], v[126:129]
	v_mfma_f32_16x16x32_bf16 v[122:125], v[176:179], v[184:187], v[122:125]
	v_mfma_f32_16x16x32_bf16 v[106:109], v[168:171], v[202:205], v[106:109]
	v_mfma_f32_16x16x32_bf16 v[110:113], v[176:179], v[202:205], v[110:113]
	v_mfma_f32_16x16x32_bf16 v[90:93], v[168:171], v[210:213], v[90:93]
	v_mfma_f32_16x16x32_bf16 v[94:97], v[176:179], v[210:213], v[94:97]
	v_mfma_f32_16x16x32_bf16 v[74:77], v[168:171], v[218:221], v[74:77]
	v_mfma_f32_16x16x32_bf16 v[78:81], v[176:179], v[218:221], v[78:81]
	v_mfma_f32_16x16x32_bf16 v[126:129], v[172:175], v[198:201], v[126:129]
	v_mfma_f32_16x16x32_bf16 v[122:125], v[180:183], v[198:201], v[122:125]
	v_mfma_f32_16x16x32_bf16 v[106:109], v[172:175], v[206:209], v[106:109]
	v_mfma_f32_16x16x32_bf16 v[110:113], v[180:183], v[206:209], v[110:113]
	v_mfma_f32_16x16x32_bf16 v[90:93], v[172:175], v[214:217], v[90:93]
	v_mfma_f32_16x16x32_bf16 v[94:97], v[180:183], v[214:217], v[94:97]
	v_mfma_f32_16x16x32_bf16 v[74:77], v[172:175], v[222:225], v[74:77]
	v_mfma_f32_16x16x32_bf16 v[78:81], v[180:183], v[222:225], v[78:81]
	s_setprio 0
	s_barrier
	s_add_i32 s60, s62, s38
	s_mov_b32 m0, s60
	ds_read_b128 v[184:187], v167 offset:16384
	ds_read_b128 v[198:201], v167 offset:17408
	ds_read_b128 v[202:205], v167 offset:18432
	ds_read_b128 v[206:209], v167 offset:19456
	ds_read_b128 v[210:213], v167 offset:20480
	ds_read_b128 v[214:217], v167 offset:21504
	ds_read_b128 v[218:221], v167 offset:22528
	ds_read_b128 v[222:225], v167 offset:23552
	global_load_lds_dwordx4 v48, s[30:31]
	s_add_i32 m0, s60, 0x2000
	s_add_u32 s68, s30, 0x40000
	s_addc_u32 s69, s31, 0
	s_add_i32 s56, s56, s38
	global_load_lds_dwordx4 v150, s[30:31]
	s_mov_b32 m0, s56
	s_nop 0
	global_load_lds_dwordx4 v48, s[68:69]
	s_add_i32 m0, s56, 0x2000
	s_nop 0
	global_load_lds_dwordx4 v150, s[68:69]
	s_mov_b32 m0, s49
	s_nop 0
	global_load_lds_dwordx4 v146, s[36:37]
	s_mov_b32 m0, s50
	s_nop 0
	global_load_lds_dwordx4 v148, s[36:37]
	s_waitcnt vmcnt(8)
	s_waitcnt lgkmcnt(0)
	s_barrier
	s_setprio 1
	s_waitcnt lgkmcnt(0)
	v_mfma_f32_16x16x32_bf16 v[62:65], v[130:133], v[184:187], v[62:65]
	v_mfma_f32_16x16x32_bf16 v[58:61], v[138:141], v[184:187], v[58:61]
	v_mfma_f32_16x16x32_bf16 v[36:39], v[130:133], v[202:205], v[36:39]
	v_mfma_f32_16x16x32_bf16 v[32:35], v[138:141], v[202:205], v[32:35]
	v_mfma_f32_16x16x32_bf16 v[20:23], v[130:133], v[210:213], v[20:23]
	v_mfma_f32_16x16x32_bf16 v[16:19], v[138:141], v[210:213], v[16:19]
	v_mfma_f32_16x16x32_bf16 v[4:7], v[130:133], v[218:221], v[4:7]
	v_mfma_f32_16x16x32_bf16 v[0:3], v[138:141], v[218:221], v[0:3]
	v_mfma_f32_16x16x32_bf16 v[62:65], v[134:137], v[198:201], v[62:65]
	v_mfma_f32_16x16x32_bf16 v[58:61], v[142:145], v[198:201], v[58:61]
	v_mfma_f32_16x16x32_bf16 v[36:39], v[134:137], v[206:209], v[36:39]
	v_mfma_f32_16x16x32_bf16 v[32:35], v[142:145], v[206:209], v[32:35]
	v_mfma_f32_16x16x32_bf16 v[20:23], v[134:137], v[214:217], v[20:23]
	v_mfma_f32_16x16x32_bf16 v[16:19], v[142:145], v[214:217], v[16:19]
	v_mfma_f32_16x16x32_bf16 v[4:7], v[134:137], v[222:225], v[4:7]
	v_mfma_f32_16x16x32_bf16 v[0:3], v[142:145], v[222:225], v[0:3]
	s_setprio 0
	s_setprio 1
	v_mfma_f32_16x16x32_bf16 v[66:69], v[168:171], v[184:187], v[66:69]
	v_mfma_f32_16x16x32_bf16 v[70:73], v[176:179], v[184:187], v[70:73]
	v_mfma_f32_16x16x32_bf16 v[40:43], v[168:171], v[202:205], v[40:43]
	v_mfma_f32_16x16x32_bf16 v[44:47], v[176:179], v[202:205], v[44:47]
	v_mfma_f32_16x16x32_bf16 v[24:27], v[168:171], v[210:213], v[24:27]
	v_mfma_f32_16x16x32_bf16 v[28:31], v[176:179], v[210:213], v[28:31]
	v_mfma_f32_16x16x32_bf16 v[8:11], v[168:171], v[218:221], v[8:11]
	v_mfma_f32_16x16x32_bf16 v[12:15], v[176:179], v[218:221], v[12:15]
	v_mfma_f32_16x16x32_bf16 v[66:69], v[172:175], v[198:201], v[66:69]
	v_mfma_f32_16x16x32_bf16 v[70:73], v[180:183], v[198:201], v[70:73]
	v_mfma_f32_16x16x32_bf16 v[40:43], v[172:175], v[206:209], v[40:43]
	v_mfma_f32_16x16x32_bf16 v[44:47], v[180:183], v[206:209], v[44:47]
	v_mfma_f32_16x16x32_bf16 v[24:27], v[172:175], v[214:217], v[24:27]
	v_mfma_f32_16x16x32_bf16 v[28:31], v[180:183], v[214:217], v[28:31]
	v_mfma_f32_16x16x32_bf16 v[8:11], v[172:175], v[222:225], v[8:11]
	v_mfma_f32_16x16x32_bf16 v[12:15], v[180:183], v[222:225], v[12:15]
	s_setprio 0
	s_barrier
	s_add_i32 s56, 0, 0x18000
	s_add_i32 s60, 0, 0x1c000
	v_add_u32_e32 v142, s56, v164
	v_add_u32_e32 v180, s60, v164
	ds_read_b128 v[130:133], v142
	ds_read_b128 v[134:137], v142 offset:1024
	ds_read_b128 v[138:141], v142 offset:2048
	ds_read_b128 v[142:145], v142 offset:3072
	ds_read_b128 v[168:171], v180
	ds_read_b128 v[172:175], v180 offset:1024
	ds_read_b128 v[176:179], v180 offset:2048
	ds_read_b128 v[180:183], v180 offset:3072
	s_add_u32 s36, s36, 0x40000
	s_addc_u32 s37, s37, 0
	s_mov_b32 m0, s52
	ds_read_b128 v[184:187], v167 offset:32768
	ds_read_b128 v[198:201], v167 offset:33792
	ds_read_b128 v[202:205], v167 offset:34816
	ds_read_b128 v[206:209], v167 offset:35840
	ds_read_b128 v[210:213], v167 offset:36864
	ds_read_b128 v[214:217], v167 offset:37888
	ds_read_b128 v[218:221], v167 offset:38912
	ds_read_b128 v[222:225], v167 offset:39936
	global_load_lds_dwordx4 v146, s[36:37]
	s_mov_b32 m0, s53
	s_nop 0
	global_load_lds_dwordx4 v148, s[36:37]
	s_waitcnt vmcnt(8)
	s_waitcnt lgkmcnt(0)
	s_barrier
	s_setprio 1
	s_waitcnt lgkmcnt(0)
	v_mfma_f32_16x16x32_bf16 v[118:121], v[130:133], v[184:187], v[118:121]
	v_mfma_f32_16x16x32_bf16 v[114:117], v[138:141], v[184:187], v[114:117]
	v_mfma_f32_16x16x32_bf16 v[102:105], v[130:133], v[202:205], v[102:105]
	v_mfma_f32_16x16x32_bf16 v[98:101], v[138:141], v[202:205], v[98:101]
	v_mfma_f32_16x16x32_bf16 v[86:89], v[130:133], v[210:213], v[86:89]
	v_mfma_f32_16x16x32_bf16 v[82:85], v[138:141], v[210:213], v[82:85]
	v_mfma_f32_16x16x32_bf16 v[54:57], v[130:133], v[218:221], v[54:57]
	v_mfma_f32_16x16x32_bf16 v[50:53], v[138:141], v[218:221], v[50:53]
	v_mfma_f32_16x16x32_bf16 v[118:121], v[134:137], v[198:201], v[118:121]
	v_mfma_f32_16x16x32_bf16 v[114:117], v[142:145], v[198:201], v[114:117]
	v_mfma_f32_16x16x32_bf16 v[102:105], v[134:137], v[206:209], v[102:105]
	v_mfma_f32_16x16x32_bf16 v[98:101], v[142:145], v[206:209], v[98:101]
	v_mfma_f32_16x16x32_bf16 v[86:89], v[134:137], v[214:217], v[86:89]
	v_mfma_f32_16x16x32_bf16 v[82:85], v[142:145], v[214:217], v[82:85]
	v_mfma_f32_16x16x32_bf16 v[54:57], v[134:137], v[222:225], v[54:57]
	v_mfma_f32_16x16x32_bf16 v[50:53], v[142:145], v[222:225], v[50:53]
	s_setprio 0
	s_setprio 1
	v_mfma_f32_16x16x32_bf16 v[126:129], v[168:171], v[184:187], v[126:129]
	v_mfma_f32_16x16x32_bf16 v[122:125], v[176:179], v[184:187], v[122:125]
	v_mfma_f32_16x16x32_bf16 v[106:109], v[168:171], v[202:205], v[106:109]
	v_mfma_f32_16x16x32_bf16 v[110:113], v[176:179], v[202:205], v[110:113]
	v_mfma_f32_16x16x32_bf16 v[90:93], v[168:171], v[210:213], v[90:93]
	v_mfma_f32_16x16x32_bf16 v[94:97], v[176:179], v[210:213], v[94:97]
	v_mfma_f32_16x16x32_bf16 v[74:77], v[168:171], v[218:221], v[74:77]
	v_mfma_f32_16x16x32_bf16 v[78:81], v[176:179], v[218:221], v[78:81]
	v_mfma_f32_16x16x32_bf16 v[126:129], v[172:175], v[198:201], v[126:129]
	v_mfma_f32_16x16x32_bf16 v[122:125], v[180:183], v[198:201], v[122:125]
	v_mfma_f32_16x16x32_bf16 v[106:109], v[172:175], v[206:209], v[106:109]
	v_mfma_f32_16x16x32_bf16 v[110:113], v[180:183], v[206:209], v[110:113]
	v_mfma_f32_16x16x32_bf16 v[90:93], v[172:175], v[214:217], v[90:93]
	v_mfma_f32_16x16x32_bf16 v[94:97], v[180:183], v[214:217], v[94:97]
	v_mfma_f32_16x16x32_bf16 v[74:77], v[172:175], v[222:225], v[74:77]
	v_mfma_f32_16x16x32_bf16 v[78:81], v[180:183], v[222:225], v[78:81]
	s_setprio 0
	s_barrier
	s_add_i32 s100, s56, s38
	s_add_u32 s30, s30, 0x80
	s_addc_u32 s31, s31, 0
	s_mov_b32 m0, s100
	ds_read_b128 v[184:187], v167 offset:49152
	ds_read_b128 v[198:201], v167 offset:50176
	ds_read_b128 v[202:205], v167 offset:51200
	ds_read_b128 v[206:209], v167 offset:52224
	ds_read_b128 v[210:213], v167 offset:53248
	ds_read_b128 v[214:217], v167 offset:54272
	ds_read_b128 v[218:221], v167 offset:55296
	ds_read_b128 v[222:225], v167 offset:56320
	global_load_lds_dwordx4 v48, s[30:31]
	s_add_i32 m0, s100, 0x2000
	s_add_u32 s68, s36, 0xfffc0080
	s_addc_u32 s69, s37, -1
	s_add_i32 s100, s60, s38
	global_load_lds_dwordx4 v150, s[30:31]
	s_add_u32 s30, s30, 0x40000
	s_addc_u32 s31, s31, 0
	s_mov_b32 m0, s100
	s_nop 0
	global_load_lds_dwordx4 v48, s[30:31]
	s_add_i32 m0, s100, 0x2000
	s_nop 0
	global_load_lds_dwordx4 v150, s[30:31]
	s_mov_b32 m0, s86
	s_nop 0
	global_load_lds_dwordx4 v146, s[68:69]
	s_mov_b32 m0, s87
	s_nop 0
	global_load_lds_dwordx4 v148, s[68:69]
	s_waitcnt vmcnt(8)
	s_waitcnt lgkmcnt(0)
	s_barrier
	s_setprio 1
	s_waitcnt lgkmcnt(0)
	v_mfma_f32_16x16x32_bf16 v[62:65], v[130:133], v[184:187], v[62:65]
	v_mfma_f32_16x16x32_bf16 v[58:61], v[138:141], v[184:187], v[58:61]
	v_mfma_f32_16x16x32_bf16 v[36:39], v[130:133], v[202:205], v[36:39]
	v_mfma_f32_16x16x32_bf16 v[32:35], v[138:141], v[202:205], v[32:35]
	v_mfma_f32_16x16x32_bf16 v[20:23], v[130:133], v[210:213], v[20:23]
	v_mfma_f32_16x16x32_bf16 v[16:19], v[138:141], v[210:213], v[16:19]
	v_mfma_f32_16x16x32_bf16 v[4:7], v[130:133], v[218:221], v[4:7]
	v_mfma_f32_16x16x32_bf16 v[0:3], v[138:141], v[218:221], v[0:3]
	v_mfma_f32_16x16x32_bf16 v[62:65], v[134:137], v[198:201], v[62:65]
	v_mfma_f32_16x16x32_bf16 v[58:61], v[142:145], v[198:201], v[58:61]
	v_mfma_f32_16x16x32_bf16 v[36:39], v[134:137], v[206:209], v[36:39]
	v_mfma_f32_16x16x32_bf16 v[32:35], v[142:145], v[206:209], v[32:35]
	v_mfma_f32_16x16x32_bf16 v[20:23], v[134:137], v[214:217], v[20:23]
	v_mfma_f32_16x16x32_bf16 v[16:19], v[142:145], v[214:217], v[16:19]
	v_mfma_f32_16x16x32_bf16 v[4:7], v[134:137], v[222:225], v[4:7]
	v_mfma_f32_16x16x32_bf16 v[0:3], v[142:145], v[222:225], v[0:3]
	s_setprio 0
	s_setprio 1
	v_mfma_f32_16x16x32_bf16 v[66:69], v[168:171], v[184:187], v[66:69]
	v_mfma_f32_16x16x32_bf16 v[70:73], v[176:179], v[184:187], v[70:73]
	v_mfma_f32_16x16x32_bf16 v[40:43], v[168:171], v[202:205], v[40:43]
	v_mfma_f32_16x16x32_bf16 v[44:47], v[176:179], v[202:205], v[44:47]
	v_mfma_f32_16x16x32_bf16 v[24:27], v[168:171], v[210:213], v[24:27]
	v_mfma_f32_16x16x32_bf16 v[28:31], v[176:179], v[210:213], v[28:31]
	v_mfma_f32_16x16x32_bf16 v[8:11], v[168:171], v[218:221], v[8:11]
	v_mfma_f32_16x16x32_bf16 v[12:15], v[176:179], v[218:221], v[12:15]
	v_mfma_f32_16x16x32_bf16 v[66:69], v[172:175], v[198:201], v[66:69]
	v_mfma_f32_16x16x32_bf16 v[70:73], v[180:183], v[198:201], v[70:73]
	v_mfma_f32_16x16x32_bf16 v[40:43], v[172:175], v[206:209], v[40:43]
	v_mfma_f32_16x16x32_bf16 v[44:47], v[180:183], v[206:209], v[44:47]
	v_mfma_f32_16x16x32_bf16 v[24:27], v[172:175], v[214:217], v[24:27]
	v_mfma_f32_16x16x32_bf16 v[28:31], v[180:183], v[214:217], v[28:31]
	v_mfma_f32_16x16x32_bf16 v[8:11], v[172:175], v[222:225], v[8:11]
	v_mfma_f32_16x16x32_bf16 v[12:15], v[180:183], v[222:225], v[12:15]
	s_setprio 0
	s_barrier
	s_add_i32 s55, s55, 2
	s_add_u32 s34, s34, 0x100
	s_addc_u32 s35, s35, 0
	s_add_u32 s46, s46, 0x100
	s_addc_u32 s54, s54, 0
	s_cmp_gt_u32 s55, 13
	s_cbranch_scc0 .LBB0_87
	s_and_b64 vcc, exec, s[20:21]
	s_cbranch_vccz .LBB0_90
	s_barrier
